# v17 + stick-breaking attn: exit-vote flags via ds_write/ds_read (one wait) instead of 8 serialized flat sc0 sc1 loads
# baseline (speedup 1.0000x reference)
.LBB0_91:
	s_mov_b64 s[14:15], exec
	v_cmp_ne_u32_e32 vcc, 0, v34
	s_and_saveexec_b64 s[18:19], s[38:39]
	s_cbranch_execz .LBB0_93
	s_cmp_eq_u64 vcc, s[14:15]
	s_cselect_b64 s[14:15], -1, 0
	v_cndmask_b32_e64 v0, 0, 1, s[14:15]
	s_nop 0
	ds_write_b32 v100, v0
.LBB0_93:
	s_or_b64 exec, exec, s[18:19]
	s_waitcnt lgkmcnt(0)
	s_barrier
	ds_read_b32 v227, v226
	ds_read_b32 v229, v228
	ds_read_b32 v231, v230
	ds_read_b32 v233, v232
	ds_read_b32 v235, v234
	ds_read_b32 v237, v236
	ds_read_b32 v239, v238
	ds_read_b32 v241, v240
	s_mov_b64 s[14:15], -1
	s_waitcnt lgkmcnt(0)
	v_and_b32_e32 v0, v229, v227
	v_bitop3_b32 v0, v0, v233, v231 bitop3:0x80
	v_bitop3_b32 v0, v0, v237, v235 bitop3:0x80
	v_bitop3_b32 v0, v0, v241, v239 bitop3:0x80
	v_cmp_eq_u32_e32 vcc, 0, v0
	v_readfirstlane_b32 s0, v0
	s_and_saveexec_b64 s[18:19], vcc
	s_cbranch_execz .LBB0_90
	v_mov_b32_e32 v0, v243
	s_mov_b32 s0, 0
	v_lshlrev_b32_e32 v35, 4, v0
	v_and_b32_e32 v36, 0xffffff80, v35
	v_bitop3_b32 v0, v35, s82, v0 bitop3:0x48
	v_add3_u32 v0, s78, v0, v36
	s_waitcnt vmcnt(0)
	ds_write_b128 v0, v[82:85]
	ds_write_b128 v0, v[86:89] offset:4096
	v_mov_b32_e32 v0, v243
	s_cmp_eq_u32 s24, 0
	v_lshlrev_b32_e32 v35, 4, v0
	v_and_b32_e32 v36, 0xffffff80, v35
	v_bitop3_b32 v35, v35, s82, v0 bitop3:0x48
	v_and_b32_e32 v0, 0x80, v0
	v_cmp_eq_u32_e32 vcc, 0, v0
	v_add3_u32 v35, s78, v35, v36
	s_nop 0
	v_cndmask_b32_e32 v39, v91, v93, vcc
	v_cndmask_b32_e32 v38, v90, v92, vcc
	v_cndmask_b32_e32 v37, v93, v91, vcc
	v_cndmask_b32_e32 v36, v92, v90, vcc
	ds_write_b128 v35, v[36:39] offset:8192
	v_cndmask_b32_e32 v39, v95, v97, vcc
	v_cndmask_b32_e32 v38, v94, v96, vcc
	v_cndmask_b32_e32 v37, v97, v95, vcc
	v_cndmask_b32_e32 v36, v96, v94, vcc
	ds_write_b128 v35, v[36:39] offset:12288
	s_waitcnt lgkmcnt(0)
	s_barrier
	s_cbranch_scc1 .LBB0_96
	s_sub_i32 s80, s24, 64
	v_mov_b32_e32 v0, v243
	s_lshl_b64 s[14:15], s[80:81], 12
	s_add_u32 s14, s8, s14
	v_ashrrev_i32_e32 v36, 3, v0
	v_lshlrev_b32_e32 v0, 4, v0
	s_addc_u32 s15, s9, s15
	v_and_b32_e32 v0, 0x70, v0
	v_ashrrev_i32_e32 v37, 31, v36
	v_lshl_add_u64 v[38:39], s[14:15], 0, v[0:1]
	v_lshlrev_b64 v[36:37], 12, v[36:37]
	v_lshl_add_u64 v[36:37], v[38:39], 0, v[36:37]
	v_add_co_u32_e32 v38, vcc, s55, v36
	v_mov_b32_e32 v0, v243
	s_nop 0
	v_addc_co_u32_e32 v39, vcc, 0, v37, vcc
	global_load_dwordx4 v[82:85], v[36:37], off offset:2048
	global_load_dwordx4 v[86:89], v[38:39], off offset:2048
	s_lshl_b64 s[14:15], s[80:81], 1
	s_add_u32 s14, s5, s14
	v_ashrrev_i32_e32 v36, 3, v0
	v_lshlrev_b32_e32 v0, 4, v0
	s_addc_u32 s15, s23, s15
	v_and_b32_e32 v0, 0x70, v0
	v_ashrrev_i32_e32 v37, 31, v36
	v_lshl_add_u64 v[38:39], s[14:15], 0, v[0:1]
	v_lshlrev_b64 v[36:37], 13, v[36:37]
	v_lshl_add_u64 v[36:37], v[38:39], 0, v[36:37]
	v_add_co_u32_e32 v38, vcc, 0x40000, v36
	s_mov_b32 s0, s24
	s_nop 0
	v_addc_co_u32_e32 v39, vcc, 0, v37, vcc
	global_load_dwordx4 v[90:93], v[36:37], off
	global_load_dwordx4 v[94:97], v[38:39], off
